# GDN: wave 7 requests its second readout group's operands at the stage top (after the staging ladder) into free VGPRs and copies them at the old request point; on top of the fence removal
# baseline (speedup 1.0000x reference)
; __device__ __forceinline__ void phase_gdn2(Frame& F, bool ctx_out, bool dry = false) {
;     ...
;                 const int s0 = st * 64; const bool isctx = s0 < TCX; const int slen = isctx ? TCX : TL, sp0 = isctx ? s0 : s0 - TCX;
;                 const int plo = d ? (slen - 64 - sp0) : sp0, rowbase = isctx ? b * TCX : ROWS_C + b * TL;
;                 int tid = tid_, lane = lane_; asm volatile("" : "+v"(tid), "+v"(lane));
;                 const int stp = st > 0 ? st - 1 : 0; const int s0p = stp * 64; const bool isctxp = s0p < TCX; const int slenp = isctxp ? TCX : TL, sp0p = isctxp ? s0p : s0p - TCX;
;                 const int plop = d ? (slenp - 64 - sp0p) : sp0p, rowbasep = isctxp ? b * TCX : ROWS_C + b * TL;
;                 const bool do_outp = (d == 1) && !dry && st > 0 && (ctx_out || !isctxp);
;                 const int tkA = (vb == 0) ? 0 : 8 * (vb - 1) + (lane >> 3);
;                 v4u pfA0, pfA1, pzA0, pzA1;
;                 { const int g8 = lane & 7; const int rowA = do_outp ? rowbasep + (plop + 63 - tkA) : 0; GDN_RD_LOAD(rowA, pfA0, pfA1, pzA0, pzA1); }
;                 const int l15 = lane & 15, q4 = lane >> 4;
;                 LAS float* s_beta = s_gate0 + (st & 1) * 208; LAS float* s_G = s_beta + 64; LAS float* s_eG = s_beta + 128; LAS float* s_eGend = s_beta + 192;
;                 {
;                     const int r0 = tid >> 4, pc = (tid & 15) * 8;
;                     const int t0 = d ? 63 - r0 : r0, t1 = d ? 31 - r0 : r0 + 32;
;                     *(LAS v4u*)(QC + t0 * GS + pc) = rawp[0]; *(LAS v4u*)(QC + t1 * GS + pc) = rawp[1];
;                     *(LAS v4u*)(KC + t0 * GS + pc) = rawp[2]; *(LAS v4u*)(KC + t1 * GS + pc) = rawp[3];
;                     const int pcs = tid & 7, tp = d ? 56 - pcs * 8 : pcs * 8;
;                     v4u x4 = rawp[4], x5 = rawp[5], x6 = rawp[6], x7 = rawp[7];
;                     if (d) {
;     ...
;                         GDN_REV(x4); GDN_REV(x5); GDN_REV(x6); GDN_REV(x7);
;     ...
;                     }
;                     const int kch = tid >> 3;
;                     *(LAS v4u*)(KCT + kch * GT + tp) = x4; *(LAS v4u*)(KCT + (kch + 64) * GT + tp) = x5;
;                     const int vch = 2 * r0 + ((tid >> 3) & 1);
;                     *(LAS v4u*)(VT + vch * GT + tp) = x6; *(LAS v4u*)(VT + (vch + 64) * GT + tp) = x7;
;                 }
;                 if (st + 1 < (TCX + TL) / 64) GDN_PREFETCH(st + 1);
.LBB0_968:
	s_min_u32 s12, s96, 1
	s_sub_i32 s13, s96, s12
	s_cmp_lg_u32 s3, 0
	s_cselect_b64 s[0:1], -1, 0
	s_lshl_b32 s12, s12, 6
	s_sub_i32 s12, s3, s12
	s_add_i32 s14, s12, 0xffffff00
	s_cmp_lt_u32 s13, 4
	s_cselect_b32 s78, s12, s14
	s_cselect_b32 s12, 0xc0, s57
	v_mov_b32_e32 v100, v112
	v_mov_b32_e32 v3, v118
	s_cselect_b32 s77, s54, s2
	s_sub_i32 s14, s12, s78
	s_and_b64 s[12:13], s[28:29], exec
	v_ashrrev_i32_e32 v147, 3, v3
	s_cselect_b32 s80, s78, s14
	v_add_u32_e32 v145, s59, v147
	v_cndmask_b32_e64 v0, v145, 0, s[38:39]
	s_or_b32 s79, s80, 63
	v_sub_u32_e32 v146, s79, v0
	v_lshlrev_b32_e32 v1, 4, v3
	v_add_u32_e32 v0, s77, v146
	s_and_b64 s[12:13], s[26:27], s[0:1]
	v_and_b32_e32 v144, 0x70, v1
	v_cndmask_b32_e64 v0, 0, v0, s[12:13]
	v_lshlrev_b32_e32 v142, 1, v144
	v_lshl_or_b32 v1, v0, 13, v142
	v_mul_lo_u32 v0, v0, s11
	v_or_b32_e32 v0, v0, v144
	v_lshlrev_b32_e32 v0, 1, v0
	global_load_dwordx4 v[76:79], v1, s[20:21] offset:16
	global_load_dwordx4 v[80:83], v1, s[20:21]
	global_load_dwordx4 v[68:71], v0, s[22:23] offset:16
	global_load_dwordx4 v[72:75], v0, s[22:23]
	v_ashrrev_i32_e32 v1, 4, v100
	v_lshlrev_b32_e32 v0, 3, v100
	v_sub_u32_e32 v84, 63, v1
	v_sub_u32_e32 v85, 31, v1
	v_add_u32_e32 v86, 32, v1
	v_and_b32_e32 v101, 0x78, v0
	v_cndmask_b32_e64 v84, v84, v1, s[28:29]
	v_cndmask_b32_e64 v85, v85, v86, s[28:29]
	v_mul_lo_u32 v84, v84, s44
	v_lshlrev_b32_e32 v86, 1, v101
	v_mul_lo_u32 v85, v85, s44
	v_add3_u32 v84, 0, v84, v86
	v_add3_u32 v85, 0, v85, v86
	s_waitcnt vmcnt(11)
	ds_write_b128 v84, v[4:7] offset:17408
	s_waitcnt vmcnt(10)
	ds_write_b128 v85, v[8:11] offset:17408
	s_waitcnt vmcnt(9)
	ds_write_b128 v84, v[12:15]
	s_waitcnt vmcnt(8)
	ds_write_b128 v85, v[16:19]
	s_waitcnt vmcnt(4)
	s_cmp_lg_u32 s33, 7
	s_cbranch_scc1 .Lgdn_nob
	v_mov_b32_e32 v206, s77
	v_or_b32_e32 v206, 55, v206
	v_sub_u32_e32 v206, v206, v145
	v_add_u32_e32 v206, s80, v206
	v_cndmask_b32_e64 v206, 0, v206, s[12:13]
	v_lshl_or_b32 v207, v206, 13, v142
	v_mul_lo_u32 v206, v206, s11
	v_or_b32_e32 v206, v206, v144
	v_lshlrev_b32_e32 v206, 1, v206
	global_load_dwordx4 v[198:201], v207, s[20:21] offset:16
	global_load_dwordx4 v[202:205], v207, s[20:21]
	global_load_dwordx4 v[190:193], v206, s[22:23] offset:16
	global_load_dwordx4 v[194:197], v206, s[22:23]
.Lgdn_nob:
	v_mov_b64_e32 v[98:99], v[34:35]
	v_mov_b64_e32 v[94:95], v[30:31]
	v_mov_b64_e32 v[90:91], v[26:27]
	v_mov_b64_e32 v[86:87], v[22:23]
	s_andn2_b64 vcc, exec, s[24:25]
	v_mov_b64_e32 v[96:97], v[32:33]
	v_mov_b64_e32 v[92:93], v[28:29]
	v_mov_b64_e32 v[88:89], v[24:25]
	v_mov_b64_e32 v[84:85], v[20:21]
	s_cbranch_vccnz .LBB0_970
	v_alignbit_b32 v84, v23, v23, 16
	v_alignbit_b32 v85, v22, v22, 16
	v_alignbit_b32 v86, v21, v21, 16
	v_alignbit_b32 v87, v20, v20, 16
	v_alignbit_b32 v88, v27, v27, 16
	v_alignbit_b32 v89, v26, v26, 16
	v_alignbit_b32 v90, v25, v25, 16
	v_alignbit_b32 v91, v24, v24, 16
	v_alignbit_b32 v92, v31, v31, 16
	v_alignbit_b32 v93, v30, v30, 16
	v_alignbit_b32 v94, v29, v29, 16
	v_alignbit_b32 v95, v28, v28, 16
	v_alignbit_b32 v96, v35, v35, 16
	v_alignbit_b32 v97, v34, v34, 16
	v_alignbit_b32 v98, v33, v33, 16
	v_alignbit_b32 v99, v32, v32, 16

; __device__ __forceinline__ void phase_gdn2(Frame& F, bool ctx_out, bool dry = false) {
;     ...
;                 if (vb == 7) {
;                     const int plo = plop, rowbase = rowbasep; const bool do_out = do_outp;
;                     v4u pfB0, pfB1, pzB0, pzB1;
;                     { const int g8 = lane & 7; const int rowB = do_outp ? rowbasep + (plop + 63 - (tkA + 8)) : 0; GDN_RD_LOAD(rowB, pfB0, pfB1, pzB0, pzB1); }
;                     if (st + 1 < (TCX + TL) / 64) GDN_GATES((st + 1) & 1);
;                     if (st > 0) { GDN_RD_OUT(tkA, pfA0, pfA1, pzA0, pzA1); GDN_RD_OUT(tkA + 8, pfB0, pfB1, pzB0, pzB1); }
.LBB0_980:
	s_or_b64 exec, exec, s[14:15]
	s_waitcnt lgkmcnt(0)
	s_barrier
	v_lshlrev_b32_e32 v143, 3, v138
	s_cmp_lt_i32 s33, 7
	s_cbranch_scc1 .LBB0_994
	s_mov_b64 s[30:31], -1
	s_mov_b64 s[14:15], 0
	s_cmp_eq_u32 s33, 7
	s_mov_b64 s[52:53], 0
	s_cbranch_scc0 .LBB0_995
	s_or_b32 s30, s77, 55
	v_sub_u32_e32 v0, s30, v145
	v_add_u32_e32 v0, s80, v0
	v_cndmask_b32_e64 v0, 0, v0, s[12:13]
	v_lshl_or_b32 v1, v0, 13, v142
	v_mul_lo_u32 v0, v0, s11
	v_or_b32_e32 v0, v0, v144
	v_lshlrev_b32_e32 v0, 1, v0
	s_waitcnt vmcnt(0)
	v_mov_b64_e32 v[92:93], v[198:199]
	v_mov_b64_e32 v[94:95], v[200:201]
	v_mov_b64_e32 v[96:97], v[202:203]
	v_mov_b64_e32 v[98:99], v[204:205]
	v_mov_b64_e32 v[84:85], v[190:191]
	v_mov_b64_e32 v[86:87], v[192:193]
	v_mov_b64_e32 v[88:89], v[194:195]
	v_mov_b64_e32 v[90:91], v[196:197]
	s_waitcnt lgkmcnt(0)
	s_andn2_b64 vcc, exec, s[50:51]
	s_cbranch_vccnz .LBB0_988
	s_waitcnt vmcnt(4)
	v_lshlrev_b32_e32 v0, 16, v135
	v_add_f32_e32 v0, v133, v0
	v_cmp_nlt_f32_e32 vcc, s8, v0
	s_and_saveexec_b64 s[30:31], vcc
	s_cbranch_execz .LBB0_985
	v_mul_f32_e32 v0, 0x3fb8aa3b, v0
	v_exp_f32_e32 v101, v0
	s_nop 0
	v_add_f32_e32 v102, 1.0, v101
	v_frexp_mant_f32_e32 v104, v102
	v_cvt_f64_f32_e32 v[0:1], v102
	v_frexp_exp_i32_f64_e32 v0, v[0:1]
	v_cmp_gt_f32_e32 vcc, s9, v104
	v_add_f32_e32 v103, -1.0, v102
	v_sub_f32_e32 v105, v103, v102
	v_subbrev_co_u32_e32 v108, vcc, 0, v0, vcc
	v_sub_u32_e32 v0, 0, v108
	v_sub_f32_e32 v103, v101, v103
	v_add_f32_e32 v105, 1.0, v105
	v_ldexp_f32 v1, v102, v0
	v_add_f32_e32 v103, v103, v105
	v_add_f32_e32 v102, -1.0, v1
	v_add_f32_e32 v104, 1.0, v1
	v_ldexp_f32 v0, v103, v0
	v_add_f32_e32 v103, 1.0, v102
	v_add_f32_e32 v105, -1.0, v104
	v_sub_f32_e32 v103, v1, v103
	v_sub_f32_e32 v1, v1, v105
	v_add_f32_e32 v103, v0, v103
	v_add_f32_e32 v0, v0, v1
	v_add_f32_e32 v109, v104, v0
	v_rcp_f32_e32 v111, v109
	v_sub_f32_e32 v1, v109, v104
	v_sub_f32_e32 v110, v0, v1
	v_add_f32_e32 v1, v102, v103
	v_mul_f32_e32 v152, v1, v111
	v_sub_f32_e32 v0, v1, v102
	v_mul_f32_e32 v102, v109, v152
	v_fma_f32 v104, v152, v109, -v102
	v_fmac_f32_e32 v104, v152, v110
	v_sub_f32_e32 v117, v103, v0
	v_add_f32_e32 v0, v102, v104
	v_sub_f32_e32 v103, v1, v0
	v_pk_add_f32 v[106:107], v[0:1], v[102:103] neg_lo:[0,1] neg_hi:[0,1]
	v_mov_b32_e32 v105, v0
	v_pk_add_f32 v[0:1], v[106:107], v[104:105] neg_lo:[0,1] neg_hi:[0,1]
	v_cmp_neq_f32_e32 vcc, s88, v101
	v_add_f32_e32 v1, v117, v1
	v_add_f32_e32 v0, v0, v1
	v_add_f32_e32 v1, v103, v0
	v_mul_f32_e32 v117, v111, v1
	v_mul_f32_e32 v102, v109, v117
	v_fma_f32 v104, v117, v109, -v102
	v_fmac_f32_e32 v104, v117, v110
	v_sub_f32_e32 v103, v103, v1
	v_add_f32_e32 v109, v0, v103
	v_add_f32_e32 v0, v102, v104
	v_sub_f32_e32 v103, v1, v0
	v_pk_add_f32 v[106:107], v[0:1], v[102:103] neg_lo:[0,1] neg_hi:[0,1]
	v_mov_b32_e32 v105, v0
	v_pk_add_f32 v[0:1], v[106:107], v[104:105] neg_lo:[0,1] neg_hi:[0,1]
	s_nop 0
	v_add_f32_e32 v1, v109, v1
	v_add_f32_e32 v0, v0, v1
	v_add_f32_e32 v1, v152, v117
	v_add_f32_e32 v0, v103, v0
	v_sub_f32_e32 v102, v1, v152
	v_mul_f32_e32 v0, v111, v0
	v_sub_f32_e32 v102, v117, v102
	v_add_f32_e32 v102, v102, v0
	v_add_f32_e32 v104, v1, v102
	v_mul_f32_e32 v105, v104, v104
	v_fmamk_f32 v0, v105, 0x3e9b6dac, v125
	v_fmaak_f32 v117, v105, v0, 0x3f2aaada
	v_cvt_f32_i32_e32 v0, v108
	v_sub_f32_e32 v1, v104, v1
	v_sub_f32_e32 v1, v102, v1
	v_ldexp_f32 v106, v1, 1
	v_mul_f32_e32 v1, v104, v105
	v_ldexp_f32 v103, v104, 1
	v_pk_mul_f32 v[104:105], v[0:1], v[116:117]
	s_nop 0
	v_fma_f32 v102, v0, s87, -v104
	v_fmac_f32_e32 v102, 0xb102e308, v0
	v_pk_add_f32 v[0:1], v[104:105], v[102:103]
	s_nop 0
	v_sub_f32_e32 v103, v1, v103
	v_sub_f32_e32 v103, v105, v103
	v_add_f32_e32 v107, v106, v103
	v_mov_b32_e32 v106, v104
	v_pk_add_f32 v[104:105], v[0:1], v[104:105] neg_lo:[0,1] neg_hi:[0,1]
	v_pk_add_f32 v[108:109], v[0:1], v[106:107]
	v_mov_b32_e32 v103, v0
	v_mov_b32_e32 v105, v109
	v_pk_add_f32 v[110:111], v[102:103], v[104:105] neg_lo:[0,1] neg_hi:[0,1]
	v_pk_add_f32 v[102:103], v[102:103], v[104:105]
	v_mov_b32_e32 v106, v107
	v_pk_add_f32 v[104:105], v[102:103], v[0:1] op_sel:[1,0] op_sel_hi:[0,1] neg_lo:[0,1] neg_hi:[0,1]
	v_pk_add_f32 v[152:153], v[108:109], v[104:105] op_sel_hi:[1,0] neg_lo:[0,1] neg_hi:[0,1]
	v_mov_b32_e32 v108, v109
	v_mov_b32_e32 v109, v103
	v_pk_mov_b32 v[104:105], v[0:1], v[104:105] op_sel:[1,0]
	v_mov_b32_e32 v107, v0
	v_pk_add_f32 v[104:105], v[108:109], v[104:105] neg_lo:[0,1] neg_hi:[0,1]
	v_mov_b32_e32 v152, v110
	v_pk_add_f32 v[0:1], v[106:107], v[104:105] neg_lo:[0,1] neg_hi:[0,1]
	v_mov_b32_e32 v111, v103
	v_pk_add_f32 v[104:105], v[152:153], v[0:1]
	s_nop 0
	v_pk_add_f32 v[106:107], v[104:105], v[104:105] op_sel:[0,1] op_sel_hi:[1,0]
	s_nop 0
	v_pk_add_f32 v[102:103], v[102:103], v[106:107] op_sel:[1,0] op_sel_hi:[0,1]
	v_mov_b32_e32 v105, v102
	v_pk_add_f32 v[108:109], v[104:105], v[110:111] neg_lo:[0,1] neg_hi:[0,1]
	v_mov_b32_e32 v1, v106
	v_sub_f32_e32 v103, v104, v108
	v_pk_add_f32 v[0:1], v[0:1], v[108:109] neg_lo:[0,1] neg_hi:[0,1]
	v_sub_f32_e32 v103, v110, v103
	v_add_f32_e32 v0, v0, v103
	v_add_f32_e32 v0, v0, v1
	v_add_f32_e32 v0, v102, v0
	v_cndmask_b32_e32 v0, v129, v0, vcc
	v_cmp_ngt_f32_e32 vcc, -1.0, v101
	s_nop 1
	v_cndmask_b32_e32 v0, v130, v0, vcc
	v_cmp_neq_f32_e32 vcc, -1.0, v101
	s_nop 1
	v_cndmask_b32_e32 v0, v131, v0, vcc
	v_cmp_lt_f32_e64 vcc, |v101|, s91
	s_nop 1
	v_cndmask_b32_e32 v0, v0, v101, vcc
